# drop conv-ssm workgroup barrier in the token-mixing phase by relocating the ssm LDS staging area
# speedup vs baseline: 1.0265x; 1.0041x over previous
; #define LAS __attribute__((address_space(3)))
; __device__ __forceinline__ int lane_id_asm() { int l; asm volatile("v_mbcnt_lo_u32_b32 %0, -1, 0\n\tv_mbcnt_hi_u32_b32 %0, -1, %0" : "=v"(l)); return l; }
; #define AIN(k) ((const float*)argp(lds, (k)))
; __global__ void __launch_bounds__(NWAVES * 64, 2) fwd_kernel(KArgs a) {
;     ...
;             for (int r_ = 0; r_ <= REP_CONV; ++r_) { const int ln2 = lane_id_asm(); for (int t = gwl; t < M / 4; t += NGW) conv_task(t, HC, (const LAS float*)lds, AIN(7) + l * 256, AIN(8) + l * 256, AIN(9) + l * 256, AC, ln2); }
;     ...
;             __syncthreads();
;             SsmW W{AIN(11) + l * 1024, AIN(12) + l * 1024, AIN(13) + l * 16, AIN(14) + (size_t)l * 16384, AIN(15) + (size_t)l * 16384, AIN(16) + (size_t)l * 16384, AIN(17) + (size_t)l * 16384, AIN(18) + l * 256};
;     ...
;             for (int r_ = 0; r_ <= REP_SSMA; ++r_) { const int ln3 = lane_id_asm(); for (int t = gwl; t < 4096; t += NGW) ssm_task_old<false>(t, W, Ub, SST, YS, lds + wave * 16384, ln3); }
.LBB0_432:
	v_readlane_b32 s0, v215, 21
	s_waitcnt lgkmcnt(0)
	v_readlane_b32 s6, v215, 22
	v_mov_b32_e32 v0, s0
	ds_read_b64 v[0:1], v0
	v_readlane_b32 s8, v215, 24
	v_readlane_b32 s18, v215, 40
	v_readlane_b32 s19, v215, 41
	s_waitcnt lgkmcnt(0)
	v_readfirstlane_b32 s10, v0
	v_mov_b32_e32 v0, s6
	v_readfirstlane_b32 s11, v1
	ds_read_b64 v[0:1], v0
	v_readlane_b32 s6, v215, 23
	s_lshl_b32 s0, s18, 10
	v_readlane_b32 s20, v215, 26
	s_waitcnt lgkmcnt(0)
	v_readfirstlane_b32 s12, v0
	v_mov_b32_e32 v0, s6
	v_readfirstlane_b32 s13, v1
	ds_read_b64 v[0:1], v0
	s_lshl_b32 s6, s18, 4
	s_mov_b32 s1, s97
	s_mov_b32 s7, s97
	s_waitcnt lgkmcnt(0)
	v_readfirstlane_b32 s14, v0
	v_mov_b32_e32 v0, s8
	v_readfirstlane_b32 s15, v1
	ds_read_b64 v[0:1], v0
	s_lshl_b64 s[8:9], s[18:19], 14
	v_readlane_b32 s18, v215, 25
	s_and_b64 vcc, exec, s[2:3]
	s_waitcnt lgkmcnt(0)
	v_readfirstlane_b32 s16, v0
	v_mov_b32_e32 v0, s18
	v_readfirstlane_b32 s17, v1
	ds_read_b64 v[0:1], v0
	s_waitcnt lgkmcnt(0)
	v_readfirstlane_b32 s18, v0
	v_mov_b32_e32 v0, s20
	v_readfirstlane_b32 s19, v1
	ds_read_b64 v[0:1], v0
	v_readlane_b32 s20, v215, 27
	s_waitcnt lgkmcnt(0)
	s_nop 0
	v_mov_b32_e32 v0, s20
	ds_read_b64 v[0:1], v0
	v_readlane_b32 s20, v215, 28
	s_waitcnt lgkmcnt(0)
	s_nop 0
	v_mov_b32_e32 v0, s20
	ds_read_b64 v[0:1], v0
	v_mbcnt_lo_u32_b32 v32, -1, 0
	v_mbcnt_hi_u32_b32 v32, -1, v32
	s_cbranch_vccz .LBB0_439
	s_lshl_b64 s[20:21], s[0:1], 2
	s_add_u32 s10, s10, s20
	s_addc_u32 s11, s11, s21
	s_add_u32 s12, s12, s20
	s_addc_u32 s13, s13, s21
	s_lshl_b64 s[20:21], s[6:7], 2
	s_add_u32 s14, s14, s20
	s_addc_u32 s15, s15, s21
	s_lshl_b64 s[20:21], s[8:9], 2
	s_add_u32 s16, s16, s20
	s_addc_u32 s17, s17, s21
	s_add_u32 s18, s18, s20
	s_addc_u32 s19, s19, s21
	s_add_u32 s26, s42, 0x9800000
	s_addc_u32 s27, s43, 0
	s_add_u32 s28, s42, 0xf800000
	s_waitcnt lgkmcnt(0)
	v_lshlrev_b32_e32 v0, 6, v32
	s_addc_u32 s29, s43, 0
	v_ashrrev_i32_e32 v33, 31, v32
	s_lshr_b32 s100, s33, 2
	s_add_i32 s100, s100, 0x8000
	v_add_u32_e32 v41, s100, v0
	s_mov_b32 s30, s54

; #define LAS __attribute__((address_space(3)))
; template <bool PASSC>
; __device__ __forceinline__ void ssm_task_old(int task, const SsmW& W, const bf16_t* U, f32x2* SST, bf16_t* YS, LAS unsigned char* wl, int lane) {
;     ...
; #pragma unroll 1
;     for (int half = 0; half < 2; ++half) {
; #pragma unroll 4
;         for (int s = 0; s < 32; ++s) {
;             const LAS f32x4* ur = (const LAS f32x4*)(uL + (half * 32 + s) * 16);
;             float br_ = 0.f, bi_ = 0.f;
; #pragma unroll
;             for (int q = 0; q < 4; ++q) { const f32x4 uv = ur[q];
; #pragma unroll
;                 for (int j = 0; j < 4; ++j) { br_ = fmaf(bbr[4 * q + j], uv[j], br_); bi_ = fmaf(bbi[4 * q + j], uv[j], bi_); } }
.LBB0_435:
	s_xor_b64 s[22:23], s[24:25], -1
	s_add_i32 s21, s100, s21
	s_mov_b32 s24, 0
